# P4 (FFN-in) epilogue: row sums of squares prefetched one tile ahead into spare VGPRs; vmcnt(0) at epilogue start removed
# speedup vs baseline: 1.0134x; 1.0052x over previous
.LBB0_596:
	s_and_b32 s16, s12, 3
	s_mov_b64 s[12:13], 0x80
	s_add_i32 m0, s44, 0x18000
	v_lshl_add_u64 v[8:9], v[8:9], 0, s[12:13]
	s_lshl_b32 s15, s14, 13
	s_lshl_b32 s18, s16, 12
	s_waitcnt vmcnt(2)
	s_barrier
	global_load_lds_dwordx4 v[8:9], off
	v_lshl_add_u64 v[6:7], v[6:7], 0, s[12:13]
	s_add_i32 m0, s44, 0x1a000
	s_add_i32 s48, s44, 0x8000
	s_add_i32 s49, s44, 0xa000
	global_load_lds_dwordx4 v[6:7], off
	v_lshl_add_u64 v[2:3], v[2:3], 0, s[12:13]
	s_mov_b32 m0, s48
	s_add_u32 s20, s30, 0x40080
	global_load_lds_dwordx4 v[2:3], off
	v_lshl_add_u64 v[2:3], v[4:5], 0, s[12:13]
	s_mov_b32 m0, s49
	s_addc_u32 s21, s31, 0
	global_load_lds_dwordx4 v[2:3], off
	s_add_i32 m0, s44, 0x1c000
	v_lshl_add_u64 v[2:3], s[20:21], 0, v[134:135]
	global_load_lds_dwordx4 v[2:3], off
	v_lshl_add_u64 v[2:3], s[20:21], 0, v[130:131]
	s_add_i32 m0, s44, 0x1e000
	s_cmpk_lt_u32 s5, 0x100
	global_load_lds_dwordx4 v[2:3], off
	v_bfe_u32 v3, v11, 4, 2
	v_and_b32_e32 v2, 15, v11
	v_lshlrev_b32_e32 v4, 4, v3
	v_lshl_or_b32 v1, s14, 6, v2
	v_lshl_or_b32 v2, v2, 6, v4
	v_lshlrev_b32_e32 v4, 2, v11
	v_and_b32_e32 v4, 32, v4
	v_bitop3_b32 v5, v2, s15, v4 bitop3:0xde
	v_bitop3_b32 v152, v2, s18, v4 bitop3:0xde
	v_and_b32_e32 v2, 16, v11
	v_lshlrev_b32_e32 v3, 2, v3
	v_add_u32_e32 v4, 60, v3
	v_cmp_eq_u32_e32 vcc, 0, v2
	s_waitcnt vmcnt(6)
	s_cselect_b64 s[14:15], -1, 0
	s_add_i32 s36, 0, 0x10000
	v_cndmask_b32_e32 v2, v4, v3, vcc
	v_lshl_add_u32 v153, s16, 4, v2
	v_lshlrev_b32_e32 v2, 14, v15
	v_and_b32_e32 v2, 0xffff8000, v2
	v_lshl_add_u32 v2, v14, 11, v2
	v_and_b32_e32 v3, 1, v15
	v_lshl_or_b32 v2, v3, 6, v2
	v_lshl_add_u32 v138, v16, 1, v2
	v_lshlrev_b32_e32 v2, 14, v10
	v_and_b32_e32 v2, 0xffff8000, v2
	v_lshl_add_u32 v2, v12, 11, v2
	v_and_b32_e32 v3, 1, v10
	v_lshl_or_b32 v2, v3, 6, v2
	s_add_i32 s37, 0, 0x14000
	s_sext_i32_i8 s1, s4
	v_mov_b32_e32 v139, v135
	v_lshl_add_u32 v140, v13, 1, v2
	v_mov_b32_e32 v141, v135
	v_mov_b64_e32 v[142:143], 0x1616
	v_mov_b64_e32 v[144:145], 0x1615
	v_add_u32_e32 v154, s36, v152
	v_add_u32_e32 v155, s37, v152
	v_add_u32_e32 v156, 0, v5
	s_movk_i32 s50, 0x1600
	s_mov_b32 s16, 0x3a800000
	s_mov_b32 s18, 0x358637bd
	s_mov_b32 s51, 0x800000
	s_barrier
	v_lshl_add_u32 v248, s0, 8, v1
	v_ashrrev_i32_e32 v249, 31, v248
	v_lshl_add_u64 v[248:249], v[248:249], 2, s[60:61]
	global_load_dword v241, v[248:249], off sc1
	global_load_dword v240, v[248:249], off offset:64 sc1
	global_load_dword v243, v[248:249], off offset:128 sc1
	global_load_dword v242, v[248:249], off offset:192 sc1
	global_load_dword v245, v[248:249], off offset:512 sc1
	global_load_dword v244, v[248:249], off offset:576 sc1
	global_load_dword v247, v[248:249], off offset:640 sc1
	global_load_dword v246, v[248:249], off offset:704 sc1
	s_branch .LBB0_599

.LBB0_605:
	s_ashr_i32 s23, s22, 31
	s_lshl_b64 s[24:25], s[22:23], 19
	s_add_u32 s24, s40, s24
	s_addc_u32 s25, s41, s25
	s_and_b64 s[26:27], s[4:5], exec
	s_cselect_b32 s23, s25, s29
	s_cselect_b32 s52, s24, s28
	s_ashr_i32 s21, s20, 31
	s_lshl_b64 s[26:27], s[20:21], 19
	s_add_u32 s26, s3, s26
	s_addc_u32 s27, s17, s27
	s_and_b64 s[38:39], s[4:5], exec
	s_cselect_b32 s21, s27, s31
	s_cselect_b32 s53, s26, s30
	s_cselect_b32 s38, s22, s0
	v_lshl_add_u32 v248, s38, 8, v1
	s_add_u32 s28, s28, 0x40080
	s_addc_u32 s29, s29, 0
	s_add_u32 s54, s30, 0x100
	v_mov_b32_e32 v2, 0
	s_addc_u32 s55, s31, 0
	s_mov_b32 s56, -2
	v_mov_b32_e32 v3, v2
	v_mov_b32_e32 v4, v2
	v_mov_b32_e32 v5, v2
	v_mov_b32_e32 v6, v2
	v_mov_b32_e32 v7, v2
	v_mov_b32_e32 v8, v2
	v_mov_b32_e32 v9, v2
	v_mov_b32_e32 v26, v2
	v_mov_b32_e32 v27, v2
	v_mov_b32_e32 v28, v2
	v_mov_b32_e32 v29, v2
	v_mov_b32_e32 v18, v2
	v_mov_b32_e32 v19, v2
	v_mov_b32_e32 v20, v2
	v_mov_b32_e32 v21, v2
	v_mov_b32_e32 v34, v2
	v_mov_b32_e32 v35, v2
	v_mov_b32_e32 v36, v2
	v_mov_b32_e32 v37, v2
	v_mov_b32_e32 v38, v2
	v_mov_b32_e32 v39, v2
	v_mov_b32_e32 v40, v2
	v_mov_b32_e32 v41, v2
	v_mov_b32_e32 v54, v2
	v_mov_b32_e32 v55, v2
	v_mov_b32_e32 v56, v2
	v_mov_b32_e32 v57, v2
	v_mov_b32_e32 v50, v2
	v_mov_b32_e32 v51, v2
	v_mov_b32_e32 v52, v2
	v_mov_b32_e32 v53, v2
	v_mov_b32_e32 v10, v2
	v_mov_b32_e32 v11, v2
	v_mov_b32_e32 v12, v2
	v_mov_b32_e32 v13, v2
	v_mov_b32_e32 v14, v2
	v_mov_b32_e32 v15, v2
	v_mov_b32_e32 v16, v2
	v_mov_b32_e32 v17, v2
	v_mov_b32_e32 v30, v2
	v_mov_b32_e32 v31, v2
	v_mov_b32_e32 v32, v2
	v_mov_b32_e32 v33, v2
	v_mov_b32_e32 v22, v2
	v_mov_b32_e32 v23, v2
	v_mov_b32_e32 v24, v2
	v_mov_b32_e32 v25, v2
	v_mov_b32_e32 v42, v2
	v_mov_b32_e32 v43, v2
	v_mov_b32_e32 v44, v2
	v_mov_b32_e32 v45, v2
	v_mov_b32_e32 v46, v2
	v_mov_b32_e32 v47, v2
	v_mov_b32_e32 v48, v2
	v_mov_b32_e32 v49, v2
	v_mov_b32_e32 v62, v2
	v_mov_b32_e32 v63, v2
	v_mov_b32_e32 v64, v2
	v_mov_b32_e32 v65, v2
	v_mov_b32_e32 v58, v2
	v_mov_b32_e32 v59, v2
	v_mov_b32_e32 v60, v2
	v_mov_b32_e32 v61, v2
	v_mov_b32_e32 v66, v2
	v_mov_b32_e32 v67, v2
	v_mov_b32_e32 v68, v2
	v_mov_b32_e32 v69, v2
	v_mov_b32_e32 v70, v2
	v_mov_b32_e32 v71, v2
	v_mov_b32_e32 v72, v2
	v_mov_b32_e32 v73, v2
	v_mov_b32_e32 v90, v2
	v_mov_b32_e32 v91, v2
	v_mov_b32_e32 v92, v2
	v_mov_b32_e32 v93, v2
	v_mov_b32_e32 v82, v2
	v_mov_b32_e32 v83, v2
	v_mov_b32_e32 v84, v2
	v_mov_b32_e32 v85, v2
	v_mov_b32_e32 v98, v2
	v_mov_b32_e32 v99, v2
	v_mov_b32_e32 v100, v2
	v_mov_b32_e32 v101, v2
	v_mov_b32_e32 v102, v2
	v_mov_b32_e32 v103, v2
	v_mov_b32_e32 v104, v2
	v_mov_b32_e32 v105, v2
	v_mov_b32_e32 v122, v2
	v_mov_b32_e32 v123, v2
	v_mov_b32_e32 v124, v2
	v_mov_b32_e32 v125, v2
	v_mov_b32_e32 v114, v2
	v_mov_b32_e32 v115, v2
	v_mov_b32_e32 v116, v2
	v_mov_b32_e32 v117, v2
	v_mov_b32_e32 v74, v2
	v_mov_b32_e32 v75, v2
	v_mov_b32_e32 v76, v2
	v_mov_b32_e32 v77, v2
	v_mov_b32_e32 v78, v2
	v_mov_b32_e32 v79, v2
	v_mov_b32_e32 v80, v2
	v_mov_b32_e32 v81, v2
	v_mov_b32_e32 v94, v2
	v_mov_b32_e32 v95, v2
	v_mov_b32_e32 v96, v2
	v_mov_b32_e32 v97, v2
	v_mov_b32_e32 v86, v2
	v_mov_b32_e32 v87, v2
	v_mov_b32_e32 v88, v2
	v_mov_b32_e32 v89, v2
	v_mov_b32_e32 v106, v2
	v_mov_b32_e32 v107, v2
	v_mov_b32_e32 v108, v2
	v_mov_b32_e32 v109, v2
	v_mov_b32_e32 v110, v2
	v_mov_b32_e32 v111, v2
	v_mov_b32_e32 v112, v2
	v_mov_b32_e32 v113, v2
	v_mov_b32_e32 v126, v2
	v_mov_b32_e32 v127, v2
	v_mov_b32_e32 v128, v2
	v_mov_b32_e32 v129, v2
	v_mov_b32_e32 v118, v2
	v_mov_b32_e32 v119, v2
	v_mov_b32_e32 v120, v2
	v_mov_b32_e32 v121, v2

.LBB0_609:
	v_lshl_add_u32 v146, s0, 8, v1
	v_ashrrev_i32_e32 v147, 31, v146
	v_ashrrev_i32_e32 v249, 31, v248
	v_mov_b32_e32 v230, v240
	v_mov_b32_e32 v231, v241
	v_mov_b32_e32 v232, v242
	v_mov_b32_e32 v233, v243
	v_mov_b32_e32 v234, v244
	v_mov_b32_e32 v235, v245
	v_mov_b32_e32 v236, v246
	v_mov_b32_e32 v237, v247
	v_lshl_add_u64 v[248:249], v[248:249], 2, s[60:61]
	global_load_dword v241, v[248:249], off sc1
	global_load_dword v240, v[248:249], off offset:64 sc1
	global_load_dword v243, v[248:249], off offset:128 sc1
	global_load_dword v242, v[248:249], off offset:192 sc1
	global_load_dword v245, v[248:249], off offset:512 sc1
	global_load_dword v244, v[248:249], off offset:576 sc1
	global_load_dword v247, v[248:249], off offset:640 sc1
	global_load_dword v246, v[248:249], off offset:704 sc1
	v_mov_b32_e32 v162, v126
	v_mov_b32_e32 v163, v118
	v_mov_b32_e32 v118, v127
	v_mov_b64_e32 v[126:127], s[18:19]
	v_mov_b32_e32 v166, v122
	v_mov_b32_e32 v167, v114
	v_mov_b32_e32 v114, v123
	v_mov_b64_e32 v[122:123], s[8:9]
	v_lshl_add_u32 v148, s1, 7, v153
	v_mov_b32_e32 v164, v128
	v_mad_i64_i32 v[172:173], s[0:1], v146, s50, v[122:123]
	v_ashrrev_i32_e32 v149, 31, v148
	v_mov_b32_e32 v165, v120
	v_mov_b32_e32 v120, v129
	v_mov_b32_e32 v168, v124
	v_mov_b32_e32 v169, v116
	v_mov_b32_e32 v116, v125
	v_lshlrev_b64 v[124:125], 1, v[148:149]
	v_pk_fma_f32 v[160:161], v[230:231], s[16:17], v[126:127] op_sel_hi:[1,0,0]
	s_nop 0
	v_mul_f32_e32 v128, 0x4b800000, v161
	v_cmp_gt_f32_e32 vcc, s51, v161
	v_mul_f32_e32 v147, 0x4b800000, v160
	v_cmp_gt_f32_e64 s[0:1], s51, v160
	v_cndmask_b32_e32 v128, v161, v128, vcc
	v_rsq_f32_e32 v157, v128
	v_cndmask_b32_e64 v147, v160, v147, s[0:1]
	v_rsq_f32_e32 v147, v147
	v_mul_f32_e32 v160, 0x45800000, v157
	v_cndmask_b32_e32 v160, v157, v160, vcc
	v_mul_f32_e32 v161, 0x45800000, v147
	v_pk_mul_f32 v[162:163], v[162:163], v[160:161] op_sel_hi:[1,0]
	v_pk_mul_f32 v[118:119], v[118:119], v[160:161] op_sel_hi:[1,0]
	v_pk_mul_f32 v[120:121], v[120:121], v[160:161] op_sel_hi:[1,0]
	v_pk_mul_f32 v[166:167], v[166:167], v[160:161] op_sel_hi:[1,0]
	v_lshl_add_u64 v[158:159], v[172:173], 0, v[124:125]
	v_pk_mul_f32 v[164:165], v[164:165], v[160:161] op_sel_hi:[1,0]
	v_pk_mul_f32 v[114:115], v[114:115], v[160:161] op_sel_hi:[1,0]
	v_pk_mul_f32 v[168:169], v[168:169], v[160:161] op_sel_hi:[1,0]
	v_pk_mul_f32 v[116:117], v[116:117], v[160:161] op_sel_hi:[1,0]
	v_mul_f32_e32 v157, 0xbfb8aa3b, v163
	v_mul_f32_e32 v160, 0xbfb8aa3b, v119
	v_mul_f32_e32 v172, 0xbfb8aa3b, v121
	v_mul_f32_e32 v173, 0xbfb8aa3b, v167
	v_mul_f32_e32 v171, 0xbfb8aa3b, v165
	v_mul_f32_e32 v174, 0xbfb8aa3b, v115
	v_mul_f32_e32 v176, 0xbfb8aa3b, v117
	v_exp_f32_e32 v157, v157
	v_exp_f32_e32 v160, v160
	v_exp_f32_e32 v172, v172
	v_exp_f32_e32 v173, v173
	v_exp_f32_e32 v171, v171
	v_exp_f32_e32 v174, v174
	v_exp_f32_e32 v176, v176
	v_add_f32_e32 v157, 1.0, v157
	v_add_f32_e32 v160, 1.0, v160
	v_add_f32_e32 v172, 1.0, v172
	v_add_f32_e32 v173, 1.0, v173
	v_add_f32_e32 v171, 1.0, v171
	v_add_f32_e32 v174, 1.0, v174
	v_add_f32_e32 v176, 1.0, v176
	v_rcp_f32_e32 v157, v157
	v_rcp_f32_e32 v160, v160
	v_rcp_f32_e32 v172, v172
	v_rcp_f32_e32 v173, v173
	v_rcp_f32_e32 v171, v171
	v_rcp_f32_e32 v174, v174
	v_rcp_f32_e32 v176, v176
	v_mul_f32_e32 v157, v163, v157
	v_mul_f32_e32 v119, v119, v160
	v_mul_f32_e32 v121, v121, v172
	v_mul_f32_e32 v163, v167, v173
	v_mul_f32_e32 v160, v165, v171
	v_mul_f32_e32 v115, v115, v174
	v_mul_f32_e32 v117, v117, v176
	v_mul_f32_e32 v118, v118, v119
	v_mul_f32_e32 v120, v120, v121
	v_mul_f32_e32 v121, v166, v163
	v_mul_f32_e32 v157, v162, v157
	v_mul_f32_e32 v119, v164, v160
	v_mul_f32_e32 v160, v114, v115
	v_mul_f32_e32 v117, v116, v117
	v_cvt_pk_bf16_f32 v114, v157, v118
	v_cvt_pk_bf16_f32 v115, v119, v120
	v_cvt_pk_bf16_f32 v116, v121, v160
	v_cndmask_b32_e64 v118, v147, v161, s[0:1]
	v_mov_b32_e32 v120, v106
	v_mov_b32_e32 v121, v110
	v_mul_f32_e32 v175, 0xbfb8aa3b, v169
	v_pk_mul_f32 v[120:121], v[120:121], v[118:119] op_sel_hi:[1,0]
	v_exp_f32_e32 v175, v175
	v_mul_f32_e32 v106, 0xbfb8aa3b, v121
	v_exp_f32_e32 v119, v106
	v_mov_b32_e32 v110, v107
	v_add_f32_e32 v175, 1.0, v175
	v_rcp_f32_e32 v175, v175
	v_pk_mul_f32 v[106:107], v[110:111], v[118:119] op_sel_hi:[1,0]
	v_permlane16_swap_b32_e32 v114, v116
	v_mul_f32_e32 v110, 0xbfb8aa3b, v107
	v_exp_f32_e32 v110, v110
	v_mul_f32_e32 v165, v169, v175
	v_mul_f32_e32 v162, v168, v165
	v_cvt_pk_bf16_f32 v117, v162, v117
	v_add_f32_e32 v111, 1.0, v119
	v_permlane16_swap_b32_e32 v115, v117
	v_add_f32_e32 v110, 1.0, v110
	global_store_dwordx4 v[158:159], v[114:117], off
	s_nop 1
	v_rcp_f32_e32 v114, v111
	v_rcp_f32_e32 v115, v110
	v_mov_b32_e32 v110, v108
	v_mov_b32_e32 v111, v112
	v_pk_mul_f32 v[110:111], v[110:111], v[118:119] op_sel_hi:[1,0]
	v_mul_f32_e32 v112, v121, v114
	v_mul_f32_e32 v108, 0xbfb8aa3b, v111
	v_exp_f32_e32 v108, v108
	v_mul_f32_e32 v114, v120, v112
	v_mov_b32_e32 v112, v109
	v_mul_f32_e32 v107, v107, v115
	v_add_f32_e32 v108, 1.0, v108
	v_rcp_f32_e32 v115, v108
	v_pk_mul_f32 v[108:109], v[112:113], v[118:119] op_sel_hi:[1,0]
	v_mul_f32_e32 v113, v106, v107
	v_mul_f32_e32 v112, 0xbfb8aa3b, v109
	v_exp_f32_e32 v112, v112
	v_mul_f32_e32 v106, v111, v115
	v_mul_f32_e32 v110, v110, v106
	v_mov_b32_e32 v107, v102
	v_add_f32_e32 v106, 1.0, v112
	v_rcp_f32_e32 v111, v106
	v_mov_b32_e32 v106, v98
	v_pk_mul_f32 v[106:107], v[106:107], v[118:119] op_sel_hi:[1,0]
	s_nop 0
	v_mul_f32_e32 v98, 0xbfb8aa3b, v107
	v_exp_f32_e32 v102, v98
	v_mul_f32_e32 v98, v109, v111
	v_mul_f32_e32 v108, v108, v98
	v_cvt_pk_bf16_f32 v98, v114, v113
	v_add_f32_e32 v102, 1.0, v102
	v_rcp_f32_e32 v109, v102
	v_mov_b32_e32 v102, v99
	v_pk_mul_f32 v[102:103], v[102:103], v[118:119] op_sel_hi:[1,0]
	v_mul_f32_e32 v107, v107, v109
	v_mul_f32_e32 v99, 0xbfb8aa3b, v103
	v_exp_f32_e32 v111, v99
	v_cvt_pk_bf16_f32 v99, v110, v108
	v_mul_f32_e32 v108, v106, v107
	v_mov_b32_e32 v107, v104
	v_add_f32_e32 v106, 1.0, v111
	v_rcp_f32_e32 v109, v106
	v_mov_b32_e32 v106, v100
	v_pk_mul_f32 v[106:107], v[106:107], v[118:119] op_sel_hi:[1,0]
	v_mov_b32_e32 v104, v101
	v_mul_f32_e32 v100, 0xbfb8aa3b, v107
	v_exp_f32_e32 v110, v100
	v_pk_mul_f32 v[100:101], v[104:105], v[118:119] op_sel_hi:[1,0]
	v_mul_f32_e32 v103, v103, v109
	v_mul_f32_e32 v104, 0xbfb8aa3b, v101
	v_exp_f32_e32 v104, v104
	v_add_f32_e32 v105, 1.0, v110
	v_rcp_f32_e32 v105, v105
	v_mul_f32_e32 v102, v102, v103
	v_add_f32_e32 v104, 1.0, v104
	v_rcp_f32_e32 v104, v104
	v_mul_f32_e32 v103, v107, v105
	v_mul_f32_e32 v103, v106, v103
	v_mul_f32_e32 v101, v101, v104
	v_mul_f32_e32 v101, v100, v101
	v_cvt_pk_bf16_f32 v100, v108, v102
	v_or_b32_e32 v102, 16, v146
	v_cvt_pk_bf16_f32 v101, v103, v101
	v_mad_i64_i32 v[102:103], s[0:1], v102, s50, v[122:123]
	v_permlane16_swap_b32_e32 v98, v100
	v_permlane16_swap_b32_e32 v99, v101
	v_lshl_add_u64 v[102:103], v[102:103], 0, v[124:125]
	global_store_dwordx4 v[102:103], v[98:101], off
	s_nop 1
	v_mov_b32_e32 v98, v94
	v_mov_b32_e32 v99, v86
	v_mov_b32_e32 v86, v95
	v_mov_b32_e32 v94, v96
	v_mov_b32_e32 v95, v88
	v_mov_b32_e32 v88, v97
	v_mov_b32_e32 v96, v90
	v_mov_b32_e32 v97, v82
	v_mov_b32_e32 v82, v91
	v_mov_b32_e32 v90, v92
	v_mov_b32_e32 v91, v84
	v_mov_b32_e32 v84, v93
	v_pk_fma_f32 v[92:93], v[232:233], s[16:17], v[126:127] op_sel_hi:[1,0,0]
	s_nop 0
	v_mul_f32_e32 v100, 0x4b800000, v93
	v_cmp_gt_f32_e32 vcc, s51, v93
	s_nop 1
	v_cndmask_b32_e32 v93, v93, v100, vcc
	v_rsq_f32_e32 v93, v93
	v_or_b32_e32 v100, 32, v146
	v_mad_i64_i32 v[100:101], s[0:1], v100, s50, v[122:123]
	v_mul_f32_e32 v102, 0x45800000, v93
	v_cndmask_b32_e32 v102, v93, v102, vcc
	v_pk_mul_f32 v[86:87], v[86:87], v[102:103] op_sel_hi:[1,0]
	v_pk_mul_f32 v[98:99], v[98:99], v[102:103] op_sel_hi:[1,0]
	v_mul_f32_e32 v103, 0xbfb8aa3b, v87
	v_exp_f32_e32 v103, v103
	v_mul_f32_e32 v93, 0xbfb8aa3b, v99
	v_exp_f32_e32 v93, v93
	v_cmp_gt_f32_e32 vcc, s51, v92
	v_add_f32_e32 v103, 1.0, v103
	v_rcp_f32_e32 v103, v103
	v_add_f32_e32 v93, 1.0, v93
	v_rcp_f32_e32 v93, v93
	v_lshl_add_u64 v[100:101], v[100:101], 0, v[124:125]
	v_pk_mul_f32 v[94:95], v[94:95], v[102:103] op_sel_hi:[1,0]
	v_pk_mul_f32 v[88:89], v[88:89], v[102:103] op_sel_hi:[1,0]
	v_mul_f32_e32 v104, 0xbfb8aa3b, v95
	v_exp_f32_e32 v104, v104
	v_mul_f32_e32 v93, v99, v93
	v_mul_f32_e32 v93, v98, v93
	v_mul_f32_e32 v99, 0xbfb8aa3b, v89
	v_add_f32_e32 v98, 1.0, v104
	v_rcp_f32_e32 v98, v98
	v_exp_f32_e32 v99, v99
	v_mul_f32_e32 v87, v87, v103
	v_mul_f32_e32 v86, v86, v87
	v_mul_f32_e32 v87, v95, v98
	v_mul_f32_e32 v87, v94, v87
	v_add_f32_e32 v94, 1.0, v99
	v_rcp_f32_e32 v98, v94
	v_pk_mul_f32 v[94:95], v[96:97], v[102:103] op_sel_hi:[1,0]
	v_pk_mul_f32 v[82:83], v[82:83], v[102:103] op_sel_hi:[1,0]
	v_mul_f32_e32 v96, 0xbfb8aa3b, v95
	v_exp_f32_e32 v96, v96
	v_mul_f32_e32 v89, v89, v98
	v_mul_f32_e32 v88, v88, v89
	v_cvt_pk_bf16_f32 v86, v93, v86
	v_add_f32_e32 v89, 1.0, v96
	v_rcp_f32_e32 v89, v89
	v_mul_f32_e32 v93, 0xbfb8aa3b, v83
	v_exp_f32_e32 v93, v93
	v_cvt_pk_bf16_f32 v87, v87, v88
	v_mul_f32_e32 v88, v95, v89
	v_mul_f32_e32 v94, v94, v88
	v_add_f32_e32 v88, 1.0, v93
	v_rcp_f32_e32 v93, v88
	v_pk_mul_f32 v[88:89], v[90:91], v[102:103] op_sel_hi:[1,0]
	v_pk_mul_f32 v[84:85], v[84:85], v[102:103] op_sel_hi:[1,0]
	v_mul_f32_e32 v90, 0xbfb8aa3b, v89
	v_exp_f32_e32 v90, v90
	v_mul_f32_e32 v91, 0xbfb8aa3b, v85
	v_exp_f32_e32 v91, v91
	v_mul_f32_e32 v83, v83, v93
	v_add_f32_e32 v90, 1.0, v90
	v_rcp_f32_e32 v90, v90
	v_mul_f32_e32 v82, v82, v83
	v_add_f32_e32 v91, 1.0, v91
	v_rcp_f32_e32 v91, v91
	v_mul_f32_e32 v83, v89, v90
	v_mul_f32_e32 v83, v88, v83
	v_cvt_pk_bf16_f32 v88, v94, v82
	v_mul_f32_e32 v82, 0x4b800000, v92
	v_cndmask_b32_e32 v82, v92, v82, vcc
	v_rsq_f32_e32 v82, v82
	v_mul_f32_e32 v85, v85, v91
	v_mul_f32_e32 v84, v84, v85
	v_cvt_pk_bf16_f32 v89, v83, v84
	v_mul_f32_e32 v83, 0x45800000, v82
	v_cndmask_b32_e32 v82, v82, v83, vcc
	v_mov_b32_e32 v84, v74
	v_mov_b32_e32 v85, v78
	v_pk_mul_f32 v[84:85], v[84:85], v[82:83] op_sel_hi:[1,0]
	v_mov_b32_e32 v78, v75
	v_mul_f32_e32 v74, 0xbfb8aa3b, v85
	v_exp_f32_e32 v83, v74
	v_permlane16_swap_b32_e32 v86, v88
	v_permlane16_swap_b32_e32 v87, v89
	v_pk_mul_f32 v[74:75], v[78:79], v[82:83] op_sel_hi:[1,0]
	v_add_f32_e32 v79, 1.0, v83
	v_mul_f32_e32 v78, 0xbfb8aa3b, v75
	v_exp_f32_e32 v78, v78
	v_rcp_f32_e32 v83, v79
	global_store_dwordx4 v[100:101], v[86:89], off
	v_mov_b32_e32 v79, v80
	v_add_f32_e32 v78, 1.0, v78
	v_rcp_f32_e32 v86, v78
	v_mov_b32_e32 v78, v76
	v_pk_mul_f32 v[78:79], v[78:79], v[82:83] op_sel_hi:[1,0]
	v_mul_f32_e32 v80, v85, v83
	v_mul_f32_e32 v76, 0xbfb8aa3b, v79
	v_exp_f32_e32 v76, v76
	v_mul_f32_e32 v83, v84, v80
	v_mov_b32_e32 v80, v77
	v_mul_f32_e32 v75, v75, v86
	v_add_f32_e32 v76, 1.0, v76
	v_rcp_f32_e32 v84, v76
	v_pk_mul_f32 v[76:77], v[80:81], v[82:83] op_sel_hi:[1,0]
	v_mul_f32_e32 v81, v74, v75
	v_mul_f32_e32 v80, 0xbfb8aa3b, v77
	v_exp_f32_e32 v80, v80
	v_mul_f32_e32 v74, v79, v84
	v_mul_f32_e32 v78, v78, v74
	v_mov_b32_e32 v75, v70
	v_add_f32_e32 v74, 1.0, v80
	v_rcp_f32_e32 v79, v74
	v_mov_b32_e32 v74, v66
	v_pk_mul_f32 v[74:75], v[74:75], v[82:83] op_sel_hi:[1,0]
	s_nop 0
	v_mul_f32_e32 v66, 0xbfb8aa3b, v75
	v_exp_f32_e32 v70, v66
	v_mul_f32_e32 v66, v77, v79
	v_mul_f32_e32 v76, v76, v66
	v_cvt_pk_bf16_f32 v66, v83, v81
	v_add_f32_e32 v70, 1.0, v70
	v_rcp_f32_e32 v77, v70
	v_mov_b32_e32 v70, v67
	v_pk_mul_f32 v[70:71], v[70:71], v[82:83] op_sel_hi:[1,0]
	v_mul_f32_e32 v75, v75, v77
	v_mul_f32_e32 v67, 0xbfb8aa3b, v71
	v_exp_f32_e32 v79, v67
	v_cvt_pk_bf16_f32 v67, v78, v76
	v_mul_f32_e32 v76, v74, v75
	v_mov_b32_e32 v75, v72
	v_add_f32_e32 v74, 1.0, v79
	v_rcp_f32_e32 v77, v74
	v_mov_b32_e32 v74, v68
	v_pk_mul_f32 v[74:75], v[74:75], v[82:83] op_sel_hi:[1,0]
	v_mov_b32_e32 v72, v69
	v_mul_f32_e32 v68, 0xbfb8aa3b, v75
	v_exp_f32_e32 v78, v68
	v_pk_mul_f32 v[68:69], v[72:73], v[82:83] op_sel_hi:[1,0]
	v_mul_f32_e32 v71, v71, v77
	v_mul_f32_e32 v72, 0xbfb8aa3b, v69
	v_exp_f32_e32 v72, v72
	v_add_f32_e32 v73, 1.0, v78
	v_rcp_f32_e32 v73, v73
	v_mul_f32_e32 v70, v70, v71
	v_add_f32_e32 v72, 1.0, v72
	v_rcp_f32_e32 v72, v72
	v_mul_f32_e32 v71, v75, v73
	v_mul_f32_e32 v71, v74, v71
	v_mul_f32_e32 v69, v69, v72
	v_mul_f32_e32 v69, v68, v69
	v_cvt_pk_bf16_f32 v68, v76, v70
	v_or_b32_e32 v70, 48, v146
	v_cvt_pk_bf16_f32 v69, v71, v69
	v_mad_i64_i32 v[70:71], s[0:1], v70, s50, v[122:123]
	v_permlane16_swap_b32_e32 v66, v68
	v_permlane16_swap_b32_e32 v67, v69
	v_lshl_add_u64 v[70:71], v[70:71], 0, v[124:125]
	global_store_dwordx4 v[70:71], v[66:69], off
	v_pk_fma_f32 v[70:71], v[234:235], s[16:17], v[126:127] op_sel_hi:[1,0,0]
	v_add_u32_e32 v72, 0x80, v146
	v_mov_b32_e32 v69, v52
	v_mul_f32_e32 v52, 0x4b800000, v71
	v_cmp_gt_f32_e32 vcc, s51, v71
	v_mov_b32_e32 v68, v56
	v_mov_b32_e32 v66, v62
	v_cndmask_b32_e32 v52, v71, v52, vcc
	v_rsq_f32_e32 v56, v52
	v_mov_b32_e32 v52, v57
	v_mov_b32_e32 v67, v58
	v_mov_b32_e32 v58, v63
	v_mul_f32_e32 v57, 0x45800000, v56
	v_cndmask_b32_e32 v56, v56, v57, vcc
	v_pk_mul_f32 v[66:67], v[66:67], v[56:57] op_sel_hi:[1,0]
	v_mov_b32_e32 v62, v64
	v_mul_f32_e32 v57, 0xbfb8aa3b, v67
	v_exp_f32_e32 v57, v57
	v_mov_b32_e32 v63, v60
	v_mov_b32_e32 v60, v65
	v_mov_b32_e32 v64, v54
	v_pk_mul_f32 v[58:59], v[58:59], v[56:57] op_sel_hi:[1,0]
	v_mov_b32_e32 v65, v50
	v_mov_b32_e32 v50, v55
	v_mad_i64_i32 v[54:55], s[0:1], v72, s50, v[122:123]
	v_mul_f32_e32 v71, 0xbfb8aa3b, v59
	v_exp_f32_e32 v71, v71
	v_lshl_add_u64 v[72:73], v[54:55], 0, v[124:125]
	v_add_f32_e32 v54, 1.0, v57
	v_rcp_f32_e32 v57, v54
	v_add_f32_e32 v54, 1.0, v71
	v_rcp_f32_e32 v71, v54
	v_cmp_gt_f32_e32 vcc, s51, v70
	v_pk_mul_f32 v[54:55], v[62:63], v[56:57] op_sel_hi:[1,0]
	v_mul_f32_e32 v57, v67, v57
	v_mul_f32_e32 v62, 0xbfb8aa3b, v55
	v_exp_f32_e32 v62, v62
	v_mul_f32_e32 v57, v66, v57
	v_pk_mul_f32 v[60:61], v[60:61], v[56:57] op_sel_hi:[1,0]
	v_mul_f32_e32 v59, v59, v71
	v_add_f32_e32 v62, 1.0, v62
	v_rcp_f32_e32 v62, v62
	v_mul_f32_e32 v63, 0xbfb8aa3b, v61
	v_exp_f32_e32 v63, v63
	v_mul_f32_e32 v66, v58, v59
	v_mul_f32_e32 v55, v55, v62
	v_mul_f32_e32 v55, v54, v55
	v_add_f32_e32 v54, 1.0, v63
	v_pk_mul_f32 v[58:59], v[64:65], v[56:57] op_sel_hi:[1,0]
	v_rcp_f32_e32 v54, v54
	v_mul_f32_e32 v62, 0xbfb8aa3b, v59
	v_exp_f32_e32 v62, v62
	v_mul_f32_e32 v54, v61, v54
	v_mul_f32_e32 v60, v60, v54
	v_cvt_pk_bf16_f32 v54, v57, v66
	v_add_f32_e32 v57, 1.0, v62
	v_rcp_f32_e32 v57, v57
	v_cvt_pk_bf16_f32 v55, v55, v60
	s_nop 0
	v_pk_mul_f32 v[50:51], v[50:51], v[56:57] op_sel_hi:[1,0]
	s_nop 0
	v_mul_f32_e32 v61, 0xbfb8aa3b, v51
	v_exp_f32_e32 v61, v61
	v_mul_f32_e32 v57, v59, v57
	v_mul_f32_e32 v57, v58, v57
	v_pk_mul_f32 v[52:53], v[52:53], v[56:57] op_sel_hi:[1,0]
	v_add_f32_e32 v58, 1.0, v61
	v_rcp_f32_e32 v60, v58
	v_pk_mul_f32 v[58:59], v[68:69], v[56:57] op_sel_hi:[1,0]
	v_mul_f32_e32 v56, 0xbfb8aa3b, v53
	v_exp_f32_e32 v56, v56
	v_mul_f32_e32 v61, 0xbfb8aa3b, v59
	v_exp_f32_e32 v61, v61
	v_mul_f32_e32 v51, v51, v60
	v_add_f32_e32 v56, 1.0, v56
	v_rcp_f32_e32 v56, v56
	v_add_f32_e32 v60, 1.0, v61
	v_mul_f32_e32 v50, v50, v51
	v_rcp_f32_e32 v60, v60
	v_mul_f32_e32 v53, v53, v56
	v_cvt_pk_bf16_f32 v56, v57, v50
	v_mul_f32_e32 v50, 0x4b800000, v70
	v_cndmask_b32_e32 v50, v70, v50, vcc
	v_rsq_f32_e32 v50, v50
	v_mul_f32_e32 v51, v59, v60
	v_mul_f32_e32 v51, v58, v51
	v_mul_f32_e32 v52, v52, v53
	v_cvt_pk_bf16_f32 v57, v51, v52
	v_mul_f32_e32 v51, 0x45800000, v50
	v_cndmask_b32_e32 v50, v50, v51, vcc
	v_mov_b32_e32 v52, v42
	v_mov_b32_e32 v53, v46
	v_pk_mul_f32 v[52:53], v[52:53], v[50:51] op_sel_hi:[1,0]
	v_mov_b32_e32 v46, v43
	v_mul_f32_e32 v42, 0xbfb8aa3b, v53
	v_exp_f32_e32 v51, v42
	v_permlane16_swap_b32_e32 v54, v56
	v_permlane16_swap_b32_e32 v55, v57
	v_pk_mul_f32 v[42:43], v[46:47], v[50:51] op_sel_hi:[1,0]
	v_add_f32_e32 v47, 1.0, v51
	v_mul_f32_e32 v46, 0xbfb8aa3b, v43
	v_exp_f32_e32 v46, v46
	v_rcp_f32_e32 v51, v47
	global_store_dwordx4 v[72:73], v[54:57], off
	v_mov_b32_e32 v47, v48
	v_add_f32_e32 v46, 1.0, v46
	v_rcp_f32_e32 v54, v46
	v_mov_b32_e32 v46, v44
	v_pk_mul_f32 v[46:47], v[46:47], v[50:51] op_sel_hi:[1,0]
	v_mul_f32_e32 v48, v53, v51
	v_mul_f32_e32 v44, 0xbfb8aa3b, v47
	v_exp_f32_e32 v44, v44
	v_mul_f32_e32 v51, v52, v48
	v_mov_b32_e32 v48, v45
	v_mul_f32_e32 v43, v43, v54
	v_add_f32_e32 v44, 1.0, v44
	v_rcp_f32_e32 v52, v44
	v_pk_mul_f32 v[44:45], v[48:49], v[50:51] op_sel_hi:[1,0]
	v_mul_f32_e32 v49, v42, v43
	v_mul_f32_e32 v48, 0xbfb8aa3b, v45
	v_exp_f32_e32 v48, v48
	v_mul_f32_e32 v42, v47, v52
	v_mul_f32_e32 v46, v46, v42
	v_mov_b32_e32 v43, v38
	v_add_f32_e32 v42, 1.0, v48
	v_rcp_f32_e32 v47, v42
	v_mov_b32_e32 v42, v34
	v_pk_mul_f32 v[42:43], v[42:43], v[50:51] op_sel_hi:[1,0]
	s_nop 0
	v_mul_f32_e32 v34, 0xbfb8aa3b, v43
	v_exp_f32_e32 v38, v34
	v_mul_f32_e32 v34, v45, v47
	v_mul_f32_e32 v44, v44, v34
	v_cvt_pk_bf16_f32 v34, v51, v49
	v_add_f32_e32 v38, 1.0, v38
	v_rcp_f32_e32 v45, v38
	v_mov_b32_e32 v38, v35
	v_pk_mul_f32 v[38:39], v[38:39], v[50:51] op_sel_hi:[1,0]
	v_mul_f32_e32 v43, v43, v45
	v_mul_f32_e32 v35, 0xbfb8aa3b, v39
	v_exp_f32_e32 v47, v35
	v_cvt_pk_bf16_f32 v35, v46, v44
	v_mul_f32_e32 v44, v42, v43
	v_mov_b32_e32 v43, v40
	v_add_f32_e32 v42, 1.0, v47
	v_rcp_f32_e32 v45, v42
	v_mov_b32_e32 v42, v36
	v_pk_mul_f32 v[42:43], v[42:43], v[50:51] op_sel_hi:[1,0]
	v_mov_b32_e32 v40, v37
	v_mul_f32_e32 v36, 0xbfb8aa3b, v43
	v_exp_f32_e32 v46, v36
	v_pk_mul_f32 v[36:37], v[40:41], v[50:51] op_sel_hi:[1,0]
	v_mul_f32_e32 v39, v39, v45
	v_mul_f32_e32 v40, 0xbfb8aa3b, v37
	v_exp_f32_e32 v40, v40
	v_add_f32_e32 v41, 1.0, v46
	v_rcp_f32_e32 v41, v41
	v_mul_f32_e32 v38, v38, v39
	v_add_f32_e32 v40, 1.0, v40
	v_rcp_f32_e32 v40, v40
	v_mul_f32_e32 v39, v43, v41
	v_mul_f32_e32 v39, v42, v39
	v_mul_f32_e32 v37, v37, v40
	v_mul_f32_e32 v37, v36, v37
	v_cvt_pk_bf16_f32 v36, v44, v38
	v_add_u32_e32 v38, 0x90, v146
	v_cvt_pk_bf16_f32 v37, v39, v37
	v_mad_i64_i32 v[38:39], s[0:1], v38, s50, v[122:123]
	v_permlane16_swap_b32_e32 v34, v36
	v_permlane16_swap_b32_e32 v35, v37
	v_lshl_add_u64 v[38:39], v[38:39], 0, v[124:125]
	global_store_dwordx4 v[38:39], v[34:37], off
	s_nop 1
	v_mov_b32_e32 v34, v30
	v_mov_b32_e32 v35, v22
	v_mov_b32_e32 v22, v31
	v_mov_b32_e32 v30, v32
	v_mov_b32_e32 v31, v24
	v_mov_b32_e32 v24, v33
	v_mov_b32_e32 v32, v26
	v_mov_b32_e32 v33, v18
	v_mov_b32_e32 v18, v27
	v_mov_b32_e32 v26, v28
	v_mov_b32_e32 v27, v20
	v_mov_b32_e32 v20, v29
	v_pk_fma_f32 v[28:29], v[236:237], s[16:17], v[126:127] op_sel_hi:[1,0,0]
	s_nop 0
	v_mul_f32_e32 v36, 0x4b800000, v29
	v_cmp_gt_f32_e32 vcc, s51, v29
	s_nop 1
	v_cndmask_b32_e32 v29, v29, v36, vcc
	v_rsq_f32_e32 v29, v29
	v_add_u32_e32 v36, 0xa0, v146
	v_mad_i64_i32 v[36:37], s[0:1], v36, s50, v[122:123]
	v_mul_f32_e32 v38, 0x45800000, v29
	v_cndmask_b32_e32 v38, v29, v38, vcc
	v_pk_mul_f32 v[22:23], v[22:23], v[38:39] op_sel_hi:[1,0]
	v_pk_mul_f32 v[34:35], v[34:35], v[38:39] op_sel_hi:[1,0]
	v_mul_f32_e32 v39, 0xbfb8aa3b, v23
	v_exp_f32_e32 v39, v39
	v_mul_f32_e32 v29, 0xbfb8aa3b, v35
	v_exp_f32_e32 v29, v29
	v_cmp_gt_f32_e32 vcc, s51, v28
	v_add_f32_e32 v39, 1.0, v39
	v_rcp_f32_e32 v39, v39
	v_add_f32_e32 v29, 1.0, v29
	v_rcp_f32_e32 v29, v29
	v_lshl_add_u64 v[36:37], v[36:37], 0, v[124:125]
	v_pk_mul_f32 v[30:31], v[30:31], v[38:39] op_sel_hi:[1,0]
	v_pk_mul_f32 v[24:25], v[24:25], v[38:39] op_sel_hi:[1,0]
	v_mul_f32_e32 v40, 0xbfb8aa3b, v31
	v_exp_f32_e32 v40, v40
	v_mul_f32_e32 v29, v35, v29
	v_mul_f32_e32 v29, v34, v29
	v_mul_f32_e32 v35, 0xbfb8aa3b, v25
	v_add_f32_e32 v34, 1.0, v40
	v_rcp_f32_e32 v34, v34
	v_exp_f32_e32 v35, v35
	v_mul_f32_e32 v23, v23, v39
	v_mul_f32_e32 v22, v22, v23
	v_mul_f32_e32 v23, v31, v34
	v_mul_f32_e32 v23, v30, v23
	v_add_f32_e32 v30, 1.0, v35
	v_rcp_f32_e32 v34, v30
	v_pk_mul_f32 v[30:31], v[32:33], v[38:39] op_sel_hi:[1,0]
	v_pk_mul_f32 v[18:19], v[18:19], v[38:39] op_sel_hi:[1,0]
	v_mul_f32_e32 v32, 0xbfb8aa3b, v31
	v_exp_f32_e32 v32, v32
	v_mul_f32_e32 v25, v25, v34
	v_mul_f32_e32 v24, v24, v25
	v_cvt_pk_bf16_f32 v22, v29, v22
	v_add_f32_e32 v25, 1.0, v32
	v_rcp_f32_e32 v25, v25
	v_mul_f32_e32 v29, 0xbfb8aa3b, v19
	v_exp_f32_e32 v29, v29
	v_cvt_pk_bf16_f32 v23, v23, v24
	v_mul_f32_e32 v24, v31, v25
	v_mul_f32_e32 v30, v30, v24
	v_add_f32_e32 v24, 1.0, v29
	v_rcp_f32_e32 v29, v24
	v_pk_mul_f32 v[24:25], v[26:27], v[38:39] op_sel_hi:[1,0]
	v_pk_mul_f32 v[20:21], v[20:21], v[38:39] op_sel_hi:[1,0]
	v_mul_f32_e32 v26, 0xbfb8aa3b, v25
	v_exp_f32_e32 v26, v26
	v_mul_f32_e32 v27, 0xbfb8aa3b, v21
	v_exp_f32_e32 v27, v27
	v_mul_f32_e32 v19, v19, v29
	v_add_f32_e32 v26, 1.0, v26
	v_rcp_f32_e32 v26, v26
	v_mul_f32_e32 v18, v18, v19
	v_add_f32_e32 v27, 1.0, v27
	v_rcp_f32_e32 v27, v27
	v_mul_f32_e32 v19, v25, v26
	v_mul_f32_e32 v19, v24, v19
	v_cvt_pk_bf16_f32 v24, v30, v18
	v_mul_f32_e32 v18, 0x4b800000, v28
	v_cndmask_b32_e32 v18, v28, v18, vcc
	v_rsq_f32_e32 v18, v18
	v_mul_f32_e32 v21, v21, v27
	v_mul_f32_e32 v20, v20, v21
	v_cvt_pk_bf16_f32 v25, v19, v20
	v_mul_f32_e32 v19, 0x45800000, v18
	v_cndmask_b32_e32 v18, v18, v19, vcc
	v_mov_b32_e32 v20, v10
	v_mov_b32_e32 v21, v14
	v_pk_mul_f32 v[20:21], v[20:21], v[18:19] op_sel_hi:[1,0]
	v_mov_b32_e32 v14, v11
	v_mul_f32_e32 v10, 0xbfb8aa3b, v21
	v_exp_f32_e32 v19, v10
	v_permlane16_swap_b32_e32 v22, v24
	v_permlane16_swap_b32_e32 v23, v25
	v_pk_mul_f32 v[10:11], v[14:15], v[18:19] op_sel_hi:[1,0]
	v_add_f32_e32 v15, 1.0, v19
	v_mul_f32_e32 v14, 0xbfb8aa3b, v11
	v_exp_f32_e32 v14, v14
	v_rcp_f32_e32 v19, v15
	global_store_dwordx4 v[36:37], v[22:25], off
	v_mov_b32_e32 v15, v16
	v_add_f32_e32 v14, 1.0, v14
	v_rcp_f32_e32 v22, v14
	v_mov_b32_e32 v14, v12
	v_pk_mul_f32 v[14:15], v[14:15], v[18:19] op_sel_hi:[1,0]
	v_mul_f32_e32 v16, v21, v19
	v_mul_f32_e32 v12, 0xbfb8aa3b, v15
	v_exp_f32_e32 v12, v12
	v_mul_f32_e32 v19, v20, v16
	v_mov_b32_e32 v16, v13
	v_mul_f32_e32 v11, v11, v22
	v_add_f32_e32 v12, 1.0, v12
	v_rcp_f32_e32 v20, v12
	v_pk_mul_f32 v[12:13], v[16:17], v[18:19] op_sel_hi:[1,0]
	v_mul_f32_e32 v17, v10, v11
	v_mul_f32_e32 v16, 0xbfb8aa3b, v13
	v_exp_f32_e32 v16, v16
	v_mul_f32_e32 v10, v15, v20
	v_mul_f32_e32 v14, v14, v10
	v_mov_b32_e32 v11, v6
	v_add_f32_e32 v10, 1.0, v16
	v_rcp_f32_e32 v15, v10
	v_mov_b32_e32 v10, v2
	v_pk_mul_f32 v[10:11], v[10:11], v[18:19] op_sel_hi:[1,0]
	s_andn2_b64 vcc, exec, s[4:5]
	v_mul_f32_e32 v2, 0xbfb8aa3b, v11
	v_exp_f32_e32 v6, v2
	v_mul_f32_e32 v2, v13, v15
	v_mul_f32_e32 v12, v12, v2
	v_cvt_pk_bf16_f32 v2, v19, v17
	v_add_f32_e32 v6, 1.0, v6
	v_rcp_f32_e32 v13, v6
	v_mov_b32_e32 v6, v3
	v_pk_mul_f32 v[6:7], v[6:7], v[18:19] op_sel_hi:[1,0]
	v_mul_f32_e32 v11, v11, v13
	v_mul_f32_e32 v3, 0xbfb8aa3b, v7
	v_exp_f32_e32 v15, v3
	v_cvt_pk_bf16_f32 v3, v14, v12
	v_mul_f32_e32 v12, v10, v11
	v_mov_b32_e32 v11, v8
	v_add_f32_e32 v10, 1.0, v15
	v_rcp_f32_e32 v13, v10
	v_mov_b32_e32 v10, v4
	v_pk_mul_f32 v[10:11], v[10:11], v[18:19] op_sel_hi:[1,0]
	v_mov_b32_e32 v8, v5
	v_mul_f32_e32 v4, 0xbfb8aa3b, v11
	v_exp_f32_e32 v14, v4
	v_pk_mul_f32 v[4:5], v[8:9], v[18:19] op_sel_hi:[1,0]
	v_mul_f32_e32 v7, v7, v13
	v_mul_f32_e32 v8, 0xbfb8aa3b, v5
	v_exp_f32_e32 v8, v8
	v_add_f32_e32 v9, 1.0, v14
	v_rcp_f32_e32 v9, v9
	v_mul_f32_e32 v6, v6, v7
	v_add_f32_e32 v8, 1.0, v8
	v_rcp_f32_e32 v8, v8
	v_mul_f32_e32 v7, v11, v9
	v_mul_f32_e32 v7, v10, v7
	v_mul_f32_e32 v5, v5, v8
	v_mul_f32_e32 v5, v4, v5
	v_cvt_pk_bf16_f32 v4, v12, v6
	v_add_u32_e32 v6, 0xb0, v146
	v_cvt_pk_bf16_f32 v5, v7, v5
	v_mad_i64_i32 v[6:7], s[0:1], v6, s50, v[122:123]
	v_permlane16_swap_b32_e32 v2, v4
	v_permlane16_swap_b32_e32 v3, v5
	v_lshl_add_u64 v[6:7], v[6:7], 0, v[124:125]
	s_mov_b64 s[0:1], -1
	global_store_dwordx4 v[6:7], v[2:5], off
	s_cbranch_vccnz .LBB0_598
	s_andn2_b64 vcc, exec, s[6:7]
	s_cbranch_vccnz .LBB0_597
	s_barrier
	s_branch .LBB0_597
